# peel + plain (non-nt) stores for SwiGLU outputs
# speedup vs baseline: 1.0267x; 1.0034x over previous
.LBB0_464:
	s_or_b64 exec, exec, s[14:15]
	s_waitcnt lgkmcnt(0)
	s_barrier
	ds_read2_b32 v[148:149], v144 offset1:16
	v_pk_mul_f32 v[120:121], v[124:125], v[120:121]
	v_pk_mul_f32 v[122:123], v[126:127], v[122:123]
	ds_read2_b32 v[138:139], v144 offset0:32 offset1:48
	ds_read2_b32 v[136:137], v144 offset0:128 offset1:144
	ds_read2_b32 v[134:135], v144 offset0:160 offset1:176
	v_pk_mul_f32 v[112:113], v[116:117], v[112:113]
	s_waitcnt lgkmcnt(0)
	v_mul_f32_e32 v150, 0xbfb8aa3b, v148
	v_pk_mul_f32 v[152:153], v[124:125], v[150:151] op_sel_hi:[1,0]
	v_pk_mul_f32 v[124:125], v[126:127], v[150:151] op_sel_hi:[1,0]
	v_exp_f32_e32 v152, v152
	v_exp_f32_e32 v124, v124
	v_exp_f32_e32 v125, v125
	v_exp_f32_e32 v153, v153
	v_mul_f32_e32 v148, v148, v148
	v_pk_mul_f32 v[126:127], v[116:117], v[150:151] op_sel_hi:[1,0]
	v_pk_add_f32 v[124:125], v[124:125], 1.0 op_sel_hi:[1,0]
	v_pk_add_f32 v[152:153], v[152:153], 1.0 op_sel_hi:[1,0]
	v_rcp_f32_e32 v124, v124
	v_rcp_f32_e32 v125, v125
	v_rcp_f32_e32 v152, v152
	v_rcp_f32_e32 v153, v153
	v_exp_f32_e32 v126, v126
	v_exp_f32_e32 v127, v127
	v_pk_mul_f32 v[122:123], v[122:123], v[148:149] op_sel_hi:[1,0]
	v_pk_mul_f32 v[120:121], v[120:121], v[148:149] op_sel_hi:[1,0]
	v_pk_mul_f32 v[122:123], v[122:123], v[124:125]
	v_pk_mul_f32 v[124:125], v[118:119], v[150:151] op_sel_hi:[1,0]
	v_pk_mul_f32 v[120:121], v[120:121], v[152:153]
	v_exp_f32_e32 v124, v124
	v_exp_f32_e32 v125, v125
	v_cvt_pk_bf16_f32 v120, v120, v121
	v_cvt_pk_bf16_f32 v121, v122, v123
	v_pk_add_f32 v[122:123], v[126:127], 1.0 op_sel_hi:[1,0]
	v_pk_add_f32 v[116:117], v[124:125], 1.0 op_sel_hi:[1,0]
	v_rcp_f32_e32 v122, v122
	v_rcp_f32_e32 v123, v123
	v_pk_mul_f32 v[114:115], v[118:119], v[114:115]
	v_rcp_f32_e32 v116, v116
	v_rcp_f32_e32 v117, v117
	v_mul_f32_e32 v118, 0xbfb8aa3b, v149
	v_pk_mul_f32 v[112:113], v[112:113], v[148:149] op_sel_hi:[1,0]
	v_pk_mul_f32 v[124:125], v[108:109], v[118:119] op_sel_hi:[1,0]
	v_pk_mul_f32 v[104:105], v[108:109], v[104:105]
	v_pk_mul_f32 v[108:109], v[110:111], v[118:119] op_sel_hi:[1,0]
	v_pk_mul_f32 v[112:113], v[112:113], v[122:123]
	v_exp_f32_e32 v108, v108
	v_exp_f32_e32 v109, v109
	v_cvt_pk_bf16_f32 v122, v112, v113
	v_pk_mul_f32 v[112:113], v[114:115], v[148:149] op_sel_hi:[1,0]
	v_lshl_or_b32 v154, s29, 7, v145
	v_pk_mul_f32 v[112:113], v[112:113], v[116:117]
	v_exp_f32_e32 v124, v124
	v_exp_f32_e32 v125, v125
	v_lshl_add_u32 v147, s30, 8, v141
	v_ashrrev_i32_e32 v155, 31, v154
	v_cvt_pk_bf16_f32 v123, v112, v113
	v_mov_b64_e32 v[112:113], s[72:73]
	v_mad_i64_i32 v[116:117], s[14:15], v147, s18, v[112:113]
	v_lshlrev_b64 v[114:115], 1, v[154:155]
	v_pk_add_f32 v[108:109], v[108:109], 1.0 op_sel_hi:[1,0]
	v_lshl_add_u64 v[116:117], v[116:117], 0, v[114:115]
	v_rcp_f32_e32 v108, v108
	v_rcp_f32_e32 v109, v109
	global_store_dwordx4 v[116:117], v[120:123], off
	v_mul_f32_e32 v116, v149, v149
	v_pk_mul_f32 v[106:107], v[110:111], v[106:107]
	v_pk_add_f32 v[120:121], v[124:125], 1.0 op_sel_hi:[1,0]
	v_pk_mul_f32 v[110:111], v[100:101], v[118:119] op_sel_hi:[1,0]
	v_rcp_f32_e32 v120, v120
	v_rcp_f32_e32 v121, v121
	v_exp_f32_e32 v110, v110
	v_exp_f32_e32 v111, v111
	v_pk_mul_f32 v[106:107], v[106:107], v[116:117] op_sel_hi:[1,0]
	v_pk_mul_f32 v[104:105], v[104:105], v[116:117] op_sel_hi:[1,0]
	v_pk_mul_f32 v[106:107], v[106:107], v[108:109]
	v_pk_mul_f32 v[108:109], v[102:103], v[118:119] op_sel_hi:[1,0]
	v_pk_mul_f32 v[104:105], v[104:105], v[120:121]
	v_exp_f32_e32 v108, v108
	v_exp_f32_e32 v109, v109
	v_cvt_pk_bf16_f32 v104, v104, v105
	v_cvt_pk_bf16_f32 v105, v106, v107
	v_pk_add_f32 v[106:107], v[110:111], 1.0 op_sel_hi:[1,0]
	v_pk_mul_f32 v[96:97], v[100:101], v[96:97]
	v_rcp_f32_e32 v106, v106
	v_rcp_f32_e32 v107, v107
	v_pk_add_f32 v[100:101], v[108:109], 1.0 op_sel_hi:[1,0]
	v_pk_mul_f32 v[96:97], v[96:97], v[116:117] op_sel_hi:[1,0]
	v_rcp_f32_e32 v100, v100
	v_rcp_f32_e32 v101, v101
	v_pk_mul_f32 v[98:99], v[102:103], v[98:99]
	v_pk_mul_f32 v[96:97], v[96:97], v[106:107]
	v_pk_mul_f32 v[88:89], v[92:93], v[88:89]
	v_cvt_pk_bf16_f32 v106, v96, v97
	v_pk_mul_f32 v[96:97], v[98:99], v[116:117] op_sel_hi:[1,0]
	v_mul_f32_e32 v98, 0xbfb8aa3b, v138
	v_pk_mul_f32 v[96:97], v[96:97], v[100:101]
	v_pk_mul_f32 v[100:101], v[92:93], v[98:99] op_sel_hi:[1,0]
	v_pk_mul_f32 v[92:93], v[94:95], v[98:99] op_sel_hi:[1,0]
	v_exp_f32_e32 v100, v100
	v_exp_f32_e32 v92, v92
	v_exp_f32_e32 v93, v93
	v_exp_f32_e32 v101, v101
	v_cvt_pk_bf16_f32 v107, v96, v97
	v_or_b32_e32 v96, 16, v147
	v_pk_add_f32 v[92:93], v[92:93], 1.0 op_sel_hi:[1,0]
	v_mad_i64_i32 v[96:97], s[14:15], v96, s18, v[112:113]
	v_rcp_f32_e32 v92, v92
	v_rcp_f32_e32 v93, v93
	v_lshl_add_u64 v[96:97], v[96:97], 0, v[114:115]
	v_pk_add_f32 v[100:101], v[100:101], 1.0 op_sel_hi:[1,0]
	global_store_dwordx4 v[96:97], v[104:107], off
	v_mul_f32_e32 v96, v138, v138
	v_rcp_f32_e32 v100, v100
	v_rcp_f32_e32 v101, v101
	v_pk_mul_f32 v[90:91], v[94:95], v[90:91]
	v_pk_mul_f32 v[94:95], v[84:85], v[98:99] op_sel_hi:[1,0]
	v_pk_mul_f32 v[90:91], v[90:91], v[96:97] op_sel_hi:[1,0]
	v_exp_f32_e32 v94, v94
	v_exp_f32_e32 v95, v95
	v_pk_mul_f32 v[90:91], v[90:91], v[92:93]
	v_pk_mul_f32 v[92:93], v[86:87], v[98:99] op_sel_hi:[1,0]
	v_pk_mul_f32 v[88:89], v[88:89], v[96:97] op_sel_hi:[1,0]
	v_exp_f32_e32 v92, v92
	v_exp_f32_e32 v93, v93
	v_pk_mul_f32 v[88:89], v[88:89], v[100:101]
	v_pk_mul_f32 v[80:81], v[84:85], v[80:81]
	v_cvt_pk_bf16_f32 v88, v88, v89
	v_cvt_pk_bf16_f32 v89, v90, v91
	v_pk_add_f32 v[90:91], v[94:95], 1.0 op_sel_hi:[1,0]
	v_pk_add_f32 v[84:85], v[92:93], 1.0 op_sel_hi:[1,0]
	v_rcp_f32_e32 v90, v90
	v_rcp_f32_e32 v91, v91
	v_rcp_f32_e32 v84, v84
	v_rcp_f32_e32 v85, v85
	v_pk_mul_f32 v[80:81], v[80:81], v[96:97] op_sel_hi:[1,0]
	v_pk_mul_f32 v[82:83], v[86:87], v[82:83]
	v_pk_mul_f32 v[80:81], v[80:81], v[90:91]
	v_pk_mul_f32 v[72:73], v[76:77], v[72:73]
	v_cvt_pk_bf16_f32 v90, v80, v81
	v_pk_mul_f32 v[80:81], v[82:83], v[96:97] op_sel_hi:[1,0]
	v_mul_f32_e32 v82, 0xbfb8aa3b, v139
	v_pk_mul_f32 v[80:81], v[80:81], v[84:85]
	v_pk_mul_f32 v[84:85], v[76:77], v[82:83] op_sel_hi:[1,0]
	v_pk_mul_f32 v[76:77], v[78:79], v[82:83] op_sel_hi:[1,0]
	v_exp_f32_e32 v84, v84
	v_exp_f32_e32 v76, v76
	v_exp_f32_e32 v77, v77
	v_exp_f32_e32 v85, v85
	v_cvt_pk_bf16_f32 v91, v80, v81
	v_or_b32_e32 v80, 32, v147
	v_pk_add_f32 v[76:77], v[76:77], 1.0 op_sel_hi:[1,0]
	v_mad_i64_i32 v[80:81], s[14:15], v80, s18, v[112:113]
	v_rcp_f32_e32 v76, v76
	v_rcp_f32_e32 v77, v77
	v_lshl_add_u64 v[80:81], v[80:81], 0, v[114:115]
	v_pk_add_f32 v[84:85], v[84:85], 1.0 op_sel_hi:[1,0]
	global_store_dwordx4 v[80:81], v[88:91], off
	v_mul_f32_e32 v80, v139, v139
	v_rcp_f32_e32 v84, v84
	v_rcp_f32_e32 v85, v85
	v_pk_mul_f32 v[74:75], v[78:79], v[74:75]
	v_pk_mul_f32 v[78:79], v[68:69], v[82:83] op_sel_hi:[1,0]
	v_pk_mul_f32 v[74:75], v[74:75], v[80:81] op_sel_hi:[1,0]
	v_exp_f32_e32 v78, v78
	v_exp_f32_e32 v79, v79
	v_pk_mul_f32 v[74:75], v[74:75], v[76:77]
	v_pk_mul_f32 v[76:77], v[70:71], v[82:83] op_sel_hi:[1,0]
	v_pk_mul_f32 v[72:73], v[72:73], v[80:81] op_sel_hi:[1,0]
	v_exp_f32_e32 v76, v76
	v_exp_f32_e32 v77, v77
	v_pk_mul_f32 v[72:73], v[72:73], v[84:85]
	v_pk_mul_f32 v[64:65], v[68:69], v[64:65]
	v_cvt_pk_bf16_f32 v72, v72, v73
	v_cvt_pk_bf16_f32 v73, v74, v75
	v_pk_add_f32 v[74:75], v[78:79], 1.0 op_sel_hi:[1,0]
	v_pk_add_f32 v[68:69], v[76:77], 1.0 op_sel_hi:[1,0]
	v_rcp_f32_e32 v74, v74
	v_rcp_f32_e32 v75, v75
	v_rcp_f32_e32 v68, v68
	v_rcp_f32_e32 v69, v69
	v_pk_mul_f32 v[64:65], v[64:65], v[80:81] op_sel_hi:[1,0]
	v_pk_mul_f32 v[66:67], v[70:71], v[66:67]
	v_pk_mul_f32 v[64:65], v[64:65], v[74:75]
	v_pk_mul_f32 v[56:57], v[60:61], v[56:57]
	v_cvt_pk_bf16_f32 v74, v64, v65
	v_pk_mul_f32 v[64:65], v[66:67], v[80:81] op_sel_hi:[1,0]
	v_mul_f32_e32 v66, 0xbfb8aa3b, v136
	v_pk_mul_f32 v[64:65], v[64:65], v[68:69]
	v_pk_mul_f32 v[68:69], v[60:61], v[66:67] op_sel_hi:[1,0]
	v_pk_mul_f32 v[60:61], v[62:63], v[66:67] op_sel_hi:[1,0]
	v_exp_f32_e32 v68, v68
	v_exp_f32_e32 v60, v60
	v_exp_f32_e32 v61, v61
	v_exp_f32_e32 v69, v69
	v_cvt_pk_bf16_f32 v75, v64, v65
	v_or_b32_e32 v64, 48, v147
	v_pk_add_f32 v[60:61], v[60:61], 1.0 op_sel_hi:[1,0]
	v_mad_i64_i32 v[64:65], s[14:15], v64, s18, v[112:113]
	v_rcp_f32_e32 v60, v60
	v_rcp_f32_e32 v61, v61
	v_lshl_add_u64 v[64:65], v[64:65], 0, v[114:115]
	v_pk_add_f32 v[68:69], v[68:69], 1.0 op_sel_hi:[1,0]
	global_store_dwordx4 v[64:65], v[72:75], off
	v_add_u32_e32 v65, 0x80, v147
	v_mul_f32_e32 v64, v136, v136
	v_rcp_f32_e32 v68, v68
	v_rcp_f32_e32 v69, v69
	v_pk_mul_f32 v[58:59], v[62:63], v[58:59]
	v_pk_mul_f32 v[62:63], v[52:53], v[66:67] op_sel_hi:[1,0]
	v_pk_mul_f32 v[58:59], v[58:59], v[64:65] op_sel_hi:[1,0]
	v_exp_f32_e32 v62, v62
	v_exp_f32_e32 v63, v63
	v_pk_mul_f32 v[58:59], v[58:59], v[60:61]
	v_pk_mul_f32 v[60:61], v[54:55], v[66:67] op_sel_hi:[1,0]
	v_pk_mul_f32 v[56:57], v[56:57], v[64:65] op_sel_hi:[1,0]
	v_exp_f32_e32 v60, v60
	v_exp_f32_e32 v61, v61
	v_pk_mul_f32 v[56:57], v[56:57], v[68:69]
	v_pk_mul_f32 v[48:49], v[52:53], v[48:49]
	v_cvt_pk_bf16_f32 v56, v56, v57
	v_cvt_pk_bf16_f32 v57, v58, v59
	v_pk_add_f32 v[58:59], v[62:63], 1.0 op_sel_hi:[1,0]
	v_pk_add_f32 v[52:53], v[60:61], 1.0 op_sel_hi:[1,0]
	v_rcp_f32_e32 v58, v58
	v_rcp_f32_e32 v59, v59
	v_rcp_f32_e32 v52, v52
	v_rcp_f32_e32 v53, v53
	v_pk_mul_f32 v[48:49], v[48:49], v[64:65] op_sel_hi:[1,0]
	v_pk_mul_f32 v[50:51], v[54:55], v[50:51]
	v_pk_mul_f32 v[48:49], v[48:49], v[58:59]
	v_pk_mul_f32 v[40:41], v[44:45], v[40:41]
	v_cvt_pk_bf16_f32 v58, v48, v49
	v_pk_mul_f32 v[48:49], v[50:51], v[64:65] op_sel_hi:[1,0]
	v_mul_f32_e32 v50, 0xbfb8aa3b, v137
	v_pk_mul_f32 v[48:49], v[48:49], v[52:53]
	v_pk_mul_f32 v[52:53], v[44:45], v[50:51] op_sel_hi:[1,0]
	v_pk_mul_f32 v[44:45], v[46:47], v[50:51] op_sel_hi:[1,0]
	v_exp_f32_e32 v52, v52
	v_exp_f32_e32 v44, v44
	v_exp_f32_e32 v45, v45
	v_exp_f32_e32 v53, v53
	v_cvt_pk_bf16_f32 v59, v48, v49
	v_mad_i64_i32 v[48:49], s[14:15], v65, s18, v[112:113]
	v_pk_add_f32 v[44:45], v[44:45], 1.0 op_sel_hi:[1,0]
	v_lshl_add_u64 v[48:49], v[48:49], 0, v[114:115]
	v_rcp_f32_e32 v44, v44
	v_rcp_f32_e32 v45, v45
	v_pk_add_f32 v[52:53], v[52:53], 1.0 op_sel_hi:[1,0]
	global_store_dwordx4 v[48:49], v[56:59], off
	v_mul_f32_e32 v48, v137, v137
	v_rcp_f32_e32 v52, v52
	v_rcp_f32_e32 v53, v53
	v_pk_mul_f32 v[42:43], v[46:47], v[42:43]
	v_pk_mul_f32 v[46:47], v[36:37], v[50:51] op_sel_hi:[1,0]
	v_pk_mul_f32 v[42:43], v[42:43], v[48:49] op_sel_hi:[1,0]
	v_exp_f32_e32 v46, v46
	v_exp_f32_e32 v47, v47
	v_pk_mul_f32 v[42:43], v[42:43], v[44:45]
	v_pk_mul_f32 v[44:45], v[38:39], v[50:51] op_sel_hi:[1,0]
	v_pk_mul_f32 v[40:41], v[40:41], v[48:49] op_sel_hi:[1,0]
	v_exp_f32_e32 v44, v44
	v_exp_f32_e32 v45, v45
	v_pk_mul_f32 v[40:41], v[40:41], v[52:53]
	v_pk_mul_f32 v[32:33], v[36:37], v[32:33]
	v_cvt_pk_bf16_f32 v40, v40, v41
	v_cvt_pk_bf16_f32 v41, v42, v43
	v_pk_add_f32 v[42:43], v[46:47], 1.0 op_sel_hi:[1,0]
	v_pk_add_f32 v[36:37], v[44:45], 1.0 op_sel_hi:[1,0]
	v_rcp_f32_e32 v42, v42
	v_rcp_f32_e32 v43, v43
	v_rcp_f32_e32 v36, v36
	v_rcp_f32_e32 v37, v37
	v_pk_mul_f32 v[32:33], v[32:33], v[48:49] op_sel_hi:[1,0]
	v_pk_mul_f32 v[34:35], v[38:39], v[34:35]
	v_pk_mul_f32 v[32:33], v[32:33], v[42:43]
	v_pk_mul_f32 v[24:25], v[28:29], v[24:25]
	v_cvt_pk_bf16_f32 v42, v32, v33
	v_pk_mul_f32 v[32:33], v[34:35], v[48:49] op_sel_hi:[1,0]
	v_mul_f32_e32 v34, 0xbfb8aa3b, v134
	v_pk_mul_f32 v[32:33], v[32:33], v[36:37]
	v_pk_mul_f32 v[36:37], v[28:29], v[34:35] op_sel_hi:[1,0]
	v_pk_mul_f32 v[28:29], v[30:31], v[34:35] op_sel_hi:[1,0]
	v_exp_f32_e32 v36, v36
	v_exp_f32_e32 v28, v28
	v_exp_f32_e32 v29, v29
	v_exp_f32_e32 v37, v37
	v_cvt_pk_bf16_f32 v43, v32, v33
	v_add_u32_e32 v32, 0x90, v147
	v_pk_add_f32 v[28:29], v[28:29], 1.0 op_sel_hi:[1,0]
	v_mad_i64_i32 v[32:33], s[14:15], v32, s18, v[112:113]
	v_rcp_f32_e32 v28, v28
	v_rcp_f32_e32 v29, v29
	v_lshl_add_u64 v[32:33], v[32:33], 0, v[114:115]
	v_pk_add_f32 v[36:37], v[36:37], 1.0 op_sel_hi:[1,0]
	global_store_dwordx4 v[32:33], v[40:43], off
	v_mul_f32_e32 v32, v134, v134
	v_rcp_f32_e32 v36, v36
	v_rcp_f32_e32 v37, v37
	v_pk_mul_f32 v[26:27], v[30:31], v[26:27]
	v_pk_mul_f32 v[30:31], v[20:21], v[34:35] op_sel_hi:[1,0]
	v_pk_mul_f32 v[26:27], v[26:27], v[32:33] op_sel_hi:[1,0]
	v_exp_f32_e32 v30, v30
	v_exp_f32_e32 v31, v31
	v_pk_mul_f32 v[26:27], v[26:27], v[28:29]
	v_pk_mul_f32 v[28:29], v[22:23], v[34:35] op_sel_hi:[1,0]
	v_pk_mul_f32 v[24:25], v[24:25], v[32:33] op_sel_hi:[1,0]
	v_exp_f32_e32 v28, v28
	v_exp_f32_e32 v29, v29
	v_pk_mul_f32 v[24:25], v[24:25], v[36:37]
	v_pk_mul_f32 v[16:17], v[20:21], v[16:17]
	v_cvt_pk_bf16_f32 v24, v24, v25
	v_cvt_pk_bf16_f32 v25, v26, v27
	v_pk_add_f32 v[26:27], v[30:31], 1.0 op_sel_hi:[1,0]
	v_pk_add_f32 v[20:21], v[28:29], 1.0 op_sel_hi:[1,0]
	v_rcp_f32_e32 v26, v26
	v_rcp_f32_e32 v27, v27
	v_rcp_f32_e32 v20, v20
	v_rcp_f32_e32 v21, v21
	v_pk_mul_f32 v[16:17], v[16:17], v[32:33] op_sel_hi:[1,0]
	v_pk_mul_f32 v[18:19], v[22:23], v[18:19]
	v_pk_mul_f32 v[16:17], v[16:17], v[26:27]
	v_pk_mul_f32 v[8:9], v[12:13], v[8:9]
	v_cvt_pk_bf16_f32 v26, v16, v17
	v_pk_mul_f32 v[16:17], v[18:19], v[32:33] op_sel_hi:[1,0]
	v_mul_f32_e32 v18, 0xbfb8aa3b, v135
	v_pk_mul_f32 v[16:17], v[16:17], v[20:21]
	v_pk_mul_f32 v[20:21], v[12:13], v[18:19] op_sel_hi:[1,0]
	v_pk_mul_f32 v[12:13], v[14:15], v[18:19] op_sel_hi:[1,0]
	v_exp_f32_e32 v20, v20
	v_exp_f32_e32 v12, v12
	v_exp_f32_e32 v13, v13
	v_exp_f32_e32 v21, v21
	v_cvt_pk_bf16_f32 v27, v16, v17
	v_add_u32_e32 v16, 0xa0, v147
	v_pk_add_f32 v[12:13], v[12:13], 1.0 op_sel_hi:[1,0]
	v_mad_i64_i32 v[16:17], s[14:15], v16, s18, v[112:113]
	v_rcp_f32_e32 v12, v12
	v_rcp_f32_e32 v13, v13
	v_lshl_add_u64 v[16:17], v[16:17], 0, v[114:115]
	v_pk_add_f32 v[20:21], v[20:21], 1.0 op_sel_hi:[1,0]
	global_store_dwordx4 v[16:17], v[24:27], off
	v_mul_f32_e32 v16, v135, v135
	v_rcp_f32_e32 v20, v20
	v_rcp_f32_e32 v21, v21
	v_pk_mul_f32 v[10:11], v[14:15], v[10:11]
	v_pk_mul_f32 v[14:15], v[4:5], v[18:19] op_sel_hi:[1,0]
	v_pk_mul_f32 v[10:11], v[10:11], v[16:17] op_sel_hi:[1,0]
	v_exp_f32_e32 v14, v14
	v_exp_f32_e32 v15, v15
	v_pk_mul_f32 v[10:11], v[10:11], v[12:13]
	v_pk_mul_f32 v[12:13], v[6:7], v[18:19] op_sel_hi:[1,0]
	v_pk_mul_f32 v[8:9], v[8:9], v[16:17] op_sel_hi:[1,0]
	v_exp_f32_e32 v12, v12
	v_exp_f32_e32 v13, v13
	v_pk_mul_f32 v[8:9], v[8:9], v[20:21]
	v_pk_mul_f32 v[0:1], v[4:5], v[0:1]
	v_cvt_pk_bf16_f32 v8, v8, v9
	v_cvt_pk_bf16_f32 v9, v10, v11
	v_pk_add_f32 v[10:11], v[14:15], 1.0 op_sel_hi:[1,0]
	v_pk_add_f32 v[4:5], v[12:13], 1.0 op_sel_hi:[1,0]
	v_rcp_f32_e32 v10, v10
	v_rcp_f32_e32 v11, v11
	v_rcp_f32_e32 v4, v4
	v_rcp_f32_e32 v5, v5
	v_pk_mul_f32 v[0:1], v[0:1], v[16:17] op_sel_hi:[1,0]
	v_pk_mul_f32 v[2:3], v[6:7], v[2:3]
	v_pk_mul_f32 v[0:1], v[0:1], v[10:11]
	s_andn2_b64 vcc, exec, s[40:41]
	v_cvt_pk_bf16_f32 v10, v0, v1
	v_pk_mul_f32 v[0:1], v[2:3], v[16:17] op_sel_hi:[1,0]
	s_nop 0
	v_pk_mul_f32 v[0:1], v[0:1], v[4:5]
	s_nop 0
	v_cvt_pk_bf16_f32 v11, v0, v1
	v_add_u32_e32 v0, 0xb0, v147
	v_mad_i64_i32 v[0:1], s[14:15], v0, s18, v[112:113]
	v_lshl_add_u64 v[0:1], v[0:1], 0, v[114:115]
	s_mov_b64 s[14:15], -1
	global_store_dwordx4 v[0:1], v[8:11], off
	s_cbranch_vccnz .LBB0_455
	s_and_b64 vcc, exec, s[36:37]
	s_cbranch_vccnz .LBB0_467
	s_lshl_b32 s14, s42, 8
	s_ashr_i32 s15, s14, 31
	v_lshl_add_u64 v[0:1], s[14:15], 2, v[130:131]
	global_load_dword v140, v[0:1], off

.LBB0_486:
	s_or_b64 exec, exec, s[14:15]
	s_waitcnt lgkmcnt(0)
	s_barrier
	ds_read2_b32 v[150:151], v145 offset1:16
	ds_read2_b32 v[140:141], v145 offset0:32 offset1:48
	ds_read2_b32 v[138:139], v145 offset0:128 offset1:144
	ds_read2_b32 v[136:137], v145 offset0:160 offset1:176
	v_pk_mul_f32 v[120:121], v[124:125], v[120:121]
	s_waitcnt lgkmcnt(0)
	v_mul_f32_e32 v152, 0xbfb8aa3b, v150
	v_pk_mul_f32 v[154:155], v[124:125], v[152:153] op_sel_hi:[1,0]
	v_pk_mul_f32 v[124:125], v[126:127], v[152:153] op_sel_hi:[1,0]
	v_mul_f32_e32 v150, v150, v150
	v_exp_f32_e32 v124, v124
	v_exp_f32_e32 v125, v125
	v_pk_mul_f32 v[122:123], v[126:127], v[122:123]
	v_pk_mul_f32 v[112:113], v[116:117], v[112:113]
	v_pk_mul_f32 v[122:123], v[122:123], v[150:151] op_sel_hi:[1,0]
	v_pk_add_f32 v[124:125], v[124:125], 1.0 op_sel_hi:[1,0]
	v_exp_f32_e32 v154, v154
	v_rcp_f32_e32 v124, v124
	v_rcp_f32_e32 v125, v125
	v_exp_f32_e32 v155, v155
	v_pk_mul_f32 v[114:115], v[118:119], v[114:115]
	v_pk_mul_f32 v[120:121], v[120:121], v[150:151] op_sel_hi:[1,0]
	v_pk_mul_f32 v[122:123], v[122:123], v[124:125]
	v_pk_mul_f32 v[124:125], v[116:117], v[152:153] op_sel_hi:[1,0]
	v_pk_mul_f32 v[116:117], v[118:119], v[152:153] op_sel_hi:[1,0]
	v_exp_f32_e32 v124, v124
	v_exp_f32_e32 v125, v125
	v_exp_f32_e32 v116, v116
	v_exp_f32_e32 v117, v117
	v_pk_add_f32 v[154:155], v[154:155], 1.0 op_sel_hi:[1,0]
	v_pk_add_f32 v[124:125], v[124:125], 1.0 op_sel_hi:[1,0]
	v_rcp_f32_e32 v154, v154
	v_pk_add_f32 v[116:117], v[116:117], 1.0 op_sel_hi:[1,0]
	v_rcp_f32_e32 v155, v155
	v_rcp_f32_e32 v124, v124
	v_rcp_f32_e32 v125, v125
	v_rcp_f32_e32 v116, v116
	v_rcp_f32_e32 v117, v117
	v_pk_mul_f32 v[112:113], v[112:113], v[150:151] op_sel_hi:[1,0]
	v_pk_mul_f32 v[114:115], v[114:115], v[150:151] op_sel_hi:[1,0]
	v_pk_mul_f32 v[120:121], v[120:121], v[154:155]
	v_pk_mul_f32 v[112:113], v[112:113], v[124:125]
	v_pk_mul_f32 v[114:115], v[114:115], v[116:117]
	v_mov_b32_e32 v116, 0
	v_mov_b32_e32 v117, 0
	v_cvt_pk_fp8_f32 v116, v120, v121
	v_cvt_pk_fp8_f32 v117, v112, v113
	v_lshl_add_u32 v148, s30, 8, v142
	v_lshl_or_b32 v134, s29, 7, v146
	v_cvt_pk_fp8_f32 v116, v122, v123 op_sel:[0,0,1]
	v_cvt_pk_fp8_f32 v117, v114, v115 op_sel:[0,0,1]
	v_mov_b64_e32 v[112:113], s[72:73]
	v_ashrrev_i32_e32 v135, 31, v134
	v_mad_i64_i32 v[114:115], s[14:15], v148, s18, v[112:113]
	v_lshl_add_u64 v[114:115], v[114:115], 0, v[134:135]
	global_store_dwordx2 v[114:115], v[116:117], off
	v_mul_f32_e32 v114, 0xbfb8aa3b, v151
	v_pk_mul_f32 v[118:119], v[108:109], v[114:115] op_sel_hi:[1,0]
	v_pk_mul_f32 v[104:105], v[108:109], v[104:105]
	v_pk_mul_f32 v[108:109], v[110:111], v[114:115] op_sel_hi:[1,0]
	v_mul_f32_e32 v116, v151, v151
	v_exp_f32_e32 v108, v108
	v_exp_f32_e32 v109, v109
	v_pk_mul_f32 v[106:107], v[110:111], v[106:107]
	v_pk_mul_f32 v[96:97], v[100:101], v[96:97]
	v_pk_mul_f32 v[106:107], v[106:107], v[116:117] op_sel_hi:[1,0]
	v_pk_add_f32 v[108:109], v[108:109], 1.0 op_sel_hi:[1,0]
	v_exp_f32_e32 v118, v118
	v_rcp_f32_e32 v108, v108
	v_rcp_f32_e32 v109, v109
	v_exp_f32_e32 v119, v119
	v_pk_mul_f32 v[98:99], v[102:103], v[98:99]
	v_pk_mul_f32 v[104:105], v[104:105], v[116:117] op_sel_hi:[1,0]
	v_pk_mul_f32 v[106:107], v[106:107], v[108:109]
	v_pk_mul_f32 v[108:109], v[100:101], v[114:115] op_sel_hi:[1,0]
	v_pk_mul_f32 v[100:101], v[102:103], v[114:115] op_sel_hi:[1,0]
	v_exp_f32_e32 v108, v108
	v_exp_f32_e32 v109, v109
	v_exp_f32_e32 v100, v100
	v_exp_f32_e32 v101, v101
	v_pk_add_f32 v[118:119], v[118:119], 1.0 op_sel_hi:[1,0]
	v_pk_add_f32 v[108:109], v[108:109], 1.0 op_sel_hi:[1,0]
	v_rcp_f32_e32 v118, v118
	v_pk_add_f32 v[100:101], v[100:101], 1.0 op_sel_hi:[1,0]
	v_rcp_f32_e32 v119, v119
	v_rcp_f32_e32 v108, v108
	v_rcp_f32_e32 v109, v109
	v_rcp_f32_e32 v100, v100
	v_rcp_f32_e32 v101, v101
	v_pk_mul_f32 v[96:97], v[96:97], v[116:117] op_sel_hi:[1,0]
	v_pk_mul_f32 v[98:99], v[98:99], v[116:117] op_sel_hi:[1,0]
	v_pk_mul_f32 v[104:105], v[104:105], v[118:119]
	v_pk_mul_f32 v[96:97], v[96:97], v[108:109]
	v_pk_mul_f32 v[98:99], v[98:99], v[100:101]
	v_mov_b32_e32 v100, 0
	v_mov_b32_e32 v101, 0
	v_cvt_pk_fp8_f32 v100, v104, v105
	v_cvt_pk_fp8_f32 v101, v96, v97
	v_or_b32_e32 v96, 16, v148
	v_mad_i64_i32 v[96:97], s[14:15], v96, s18, v[112:113]
	v_cvt_pk_fp8_f32 v100, v106, v107 op_sel:[0,0,1]
	v_cvt_pk_fp8_f32 v101, v98, v99 op_sel:[0,0,1]
	v_lshl_add_u64 v[96:97], v[96:97], 0, v[134:135]
	v_pk_mul_f32 v[88:89], v[92:93], v[88:89]
	v_mul_f32_e32 v98, v140, v140
	global_store_dwordx2 v[96:97], v[100:101], off
	v_mul_f32_e32 v96, 0xbfb8aa3b, v140
	v_pk_mul_f32 v[100:101], v[92:93], v[96:97] op_sel_hi:[1,0]
	v_pk_mul_f32 v[92:93], v[94:95], v[96:97] op_sel_hi:[1,0]
	v_pk_mul_f32 v[90:91], v[94:95], v[90:91]
	v_exp_f32_e32 v92, v92
	v_exp_f32_e32 v93, v93
	v_pk_mul_f32 v[90:91], v[90:91], v[98:99] op_sel_hi:[1,0]
	v_pk_mul_f32 v[80:81], v[84:85], v[80:81]
	v_exp_f32_e32 v100, v100
	v_pk_add_f32 v[92:93], v[92:93], 1.0 op_sel_hi:[1,0]
	v_exp_f32_e32 v101, v101
	v_rcp_f32_e32 v92, v92
	v_rcp_f32_e32 v93, v93
	v_pk_mul_f32 v[82:83], v[86:87], v[82:83]
	v_pk_add_f32 v[100:101], v[100:101], 1.0 op_sel_hi:[1,0]
	v_pk_mul_f32 v[88:89], v[88:89], v[98:99] op_sel_hi:[1,0]
	v_pk_mul_f32 v[90:91], v[90:91], v[92:93]
	v_pk_mul_f32 v[92:93], v[84:85], v[96:97] op_sel_hi:[1,0]
	v_pk_mul_f32 v[84:85], v[86:87], v[96:97] op_sel_hi:[1,0]
	v_exp_f32_e32 v92, v92
	v_exp_f32_e32 v93, v93
	v_exp_f32_e32 v84, v84
	v_exp_f32_e32 v85, v85
	v_rcp_f32_e32 v100, v100
	v_pk_add_f32 v[92:93], v[92:93], 1.0 op_sel_hi:[1,0]
	v_rcp_f32_e32 v101, v101
	v_pk_add_f32 v[84:85], v[84:85], 1.0 op_sel_hi:[1,0]
	v_rcp_f32_e32 v92, v92
	v_rcp_f32_e32 v93, v93
	v_rcp_f32_e32 v84, v84
	v_rcp_f32_e32 v85, v85
	v_pk_mul_f32 v[80:81], v[80:81], v[98:99] op_sel_hi:[1,0]
	v_pk_mul_f32 v[82:83], v[82:83], v[98:99] op_sel_hi:[1,0]
	v_pk_mul_f32 v[88:89], v[88:89], v[100:101]
	v_pk_mul_f32 v[80:81], v[80:81], v[92:93]
	v_pk_mul_f32 v[82:83], v[82:83], v[84:85]
	v_mov_b32_e32 v84, 0
	v_mov_b32_e32 v85, 0
	v_cvt_pk_fp8_f32 v84, v88, v89
	v_cvt_pk_fp8_f32 v85, v80, v81
	v_or_b32_e32 v80, 32, v148
	v_mad_i64_i32 v[80:81], s[14:15], v80, s18, v[112:113]
	v_cvt_pk_fp8_f32 v84, v90, v91 op_sel:[0,0,1]
	v_cvt_pk_fp8_f32 v85, v82, v83 op_sel:[0,0,1]
	v_lshl_add_u64 v[80:81], v[80:81], 0, v[134:135]
	v_pk_mul_f32 v[72:73], v[76:77], v[72:73]
	v_mul_f32_e32 v82, v141, v141
	global_store_dwordx2 v[80:81], v[84:85], off
	v_mul_f32_e32 v80, 0xbfb8aa3b, v141
	v_pk_mul_f32 v[84:85], v[76:77], v[80:81] op_sel_hi:[1,0]
	v_pk_mul_f32 v[76:77], v[78:79], v[80:81] op_sel_hi:[1,0]
	v_pk_mul_f32 v[74:75], v[78:79], v[74:75]
	v_exp_f32_e32 v76, v76
	v_exp_f32_e32 v77, v77
	v_pk_mul_f32 v[74:75], v[74:75], v[82:83] op_sel_hi:[1,0]
	v_pk_mul_f32 v[64:65], v[68:69], v[64:65]
	v_exp_f32_e32 v84, v84
	v_pk_add_f32 v[76:77], v[76:77], 1.0 op_sel_hi:[1,0]
	v_exp_f32_e32 v85, v85
	v_rcp_f32_e32 v76, v76
	v_rcp_f32_e32 v77, v77
	v_pk_mul_f32 v[66:67], v[70:71], v[66:67]
	v_pk_add_f32 v[84:85], v[84:85], 1.0 op_sel_hi:[1,0]
	v_pk_mul_f32 v[72:73], v[72:73], v[82:83] op_sel_hi:[1,0]
	v_pk_mul_f32 v[74:75], v[74:75], v[76:77]
	v_pk_mul_f32 v[76:77], v[68:69], v[80:81] op_sel_hi:[1,0]
	v_pk_mul_f32 v[68:69], v[70:71], v[80:81] op_sel_hi:[1,0]
	v_exp_f32_e32 v76, v76
	v_exp_f32_e32 v77, v77
	v_exp_f32_e32 v68, v68
	v_exp_f32_e32 v69, v69
	v_rcp_f32_e32 v84, v84
	v_pk_add_f32 v[76:77], v[76:77], 1.0 op_sel_hi:[1,0]
	v_rcp_f32_e32 v85, v85
	v_pk_add_f32 v[68:69], v[68:69], 1.0 op_sel_hi:[1,0]
	v_rcp_f32_e32 v76, v76
	v_rcp_f32_e32 v77, v77
	v_rcp_f32_e32 v68, v68
	v_rcp_f32_e32 v69, v69
	v_pk_mul_f32 v[64:65], v[64:65], v[82:83] op_sel_hi:[1,0]
	v_pk_mul_f32 v[66:67], v[66:67], v[82:83] op_sel_hi:[1,0]
	v_pk_mul_f32 v[72:73], v[72:73], v[84:85]
	v_pk_mul_f32 v[64:65], v[64:65], v[76:77]
	v_pk_mul_f32 v[66:67], v[66:67], v[68:69]
	v_mov_b32_e32 v68, 0
	v_mov_b32_e32 v69, 0
	v_cvt_pk_fp8_f32 v68, v72, v73
	v_cvt_pk_fp8_f32 v69, v64, v65
	v_or_b32_e32 v64, 48, v148
	v_mad_i64_i32 v[64:65], s[14:15], v64, s18, v[112:113]
	v_cvt_pk_fp8_f32 v68, v74, v75 op_sel:[0,0,1]
	v_cvt_pk_fp8_f32 v69, v66, v67 op_sel:[0,0,1]
	v_lshl_add_u64 v[64:65], v[64:65], 0, v[134:135]
	v_pk_mul_f32 v[56:57], v[60:61], v[56:57]
	v_mul_f32_e32 v66, v138, v138
	global_store_dwordx2 v[64:65], v[68:69], off
	v_add_u32_e32 v65, 0x80, v148
	v_mul_f32_e32 v64, 0xbfb8aa3b, v138
	v_pk_mul_f32 v[68:69], v[60:61], v[64:65] op_sel_hi:[1,0]
	v_pk_mul_f32 v[60:61], v[62:63], v[64:65] op_sel_hi:[1,0]
	v_pk_mul_f32 v[58:59], v[62:63], v[58:59]
	v_exp_f32_e32 v60, v60
	v_exp_f32_e32 v61, v61
	v_pk_mul_f32 v[58:59], v[58:59], v[66:67] op_sel_hi:[1,0]
	v_pk_mul_f32 v[48:49], v[52:53], v[48:49]
	v_exp_f32_e32 v68, v68
	v_pk_add_f32 v[60:61], v[60:61], 1.0 op_sel_hi:[1,0]
	v_exp_f32_e32 v69, v69
	v_rcp_f32_e32 v60, v60
	v_rcp_f32_e32 v61, v61
	v_pk_mul_f32 v[50:51], v[54:55], v[50:51]
	v_pk_add_f32 v[68:69], v[68:69], 1.0 op_sel_hi:[1,0]
	v_pk_mul_f32 v[56:57], v[56:57], v[66:67] op_sel_hi:[1,0]
	v_pk_mul_f32 v[58:59], v[58:59], v[60:61]
	v_pk_mul_f32 v[60:61], v[52:53], v[64:65] op_sel_hi:[1,0]
	v_pk_mul_f32 v[52:53], v[54:55], v[64:65] op_sel_hi:[1,0]
	v_exp_f32_e32 v60, v60
	v_exp_f32_e32 v61, v61
	v_exp_f32_e32 v52, v52
	v_exp_f32_e32 v53, v53
	v_rcp_f32_e32 v68, v68
	v_pk_add_f32 v[60:61], v[60:61], 1.0 op_sel_hi:[1,0]
	v_rcp_f32_e32 v69, v69
	v_pk_add_f32 v[52:53], v[52:53], 1.0 op_sel_hi:[1,0]
	v_rcp_f32_e32 v60, v60
	v_rcp_f32_e32 v61, v61
	v_rcp_f32_e32 v52, v52
	v_rcp_f32_e32 v53, v53
	v_pk_mul_f32 v[48:49], v[48:49], v[66:67] op_sel_hi:[1,0]
	v_pk_mul_f32 v[50:51], v[50:51], v[66:67] op_sel_hi:[1,0]
	v_pk_mul_f32 v[56:57], v[56:57], v[68:69]
	v_pk_mul_f32 v[48:49], v[48:49], v[60:61]
	v_pk_mul_f32 v[50:51], v[50:51], v[52:53]
	v_mov_b32_e32 v52, 0
	v_mov_b32_e32 v53, 0
	v_cvt_pk_fp8_f32 v52, v56, v57
	v_cvt_pk_fp8_f32 v53, v48, v49
	v_mad_i64_i32 v[48:49], s[14:15], v65, s18, v[112:113]
	v_cvt_pk_fp8_f32 v52, v58, v59 op_sel:[0,0,1]
	v_cvt_pk_fp8_f32 v53, v50, v51 op_sel:[0,0,1]
	v_lshl_add_u64 v[48:49], v[48:49], 0, v[134:135]
	v_pk_mul_f32 v[40:41], v[44:45], v[40:41]
	v_mul_f32_e32 v50, v139, v139
	global_store_dwordx2 v[48:49], v[52:53], off
	v_mul_f32_e32 v48, 0xbfb8aa3b, v139
	v_pk_mul_f32 v[52:53], v[44:45], v[48:49] op_sel_hi:[1,0]
	v_pk_mul_f32 v[44:45], v[46:47], v[48:49] op_sel_hi:[1,0]
	v_pk_mul_f32 v[42:43], v[46:47], v[42:43]
	v_exp_f32_e32 v44, v44
	v_exp_f32_e32 v45, v45
	v_pk_mul_f32 v[42:43], v[42:43], v[50:51] op_sel_hi:[1,0]
	v_pk_mul_f32 v[32:33], v[36:37], v[32:33]
	v_exp_f32_e32 v52, v52
	v_pk_add_f32 v[44:45], v[44:45], 1.0 op_sel_hi:[1,0]
	v_exp_f32_e32 v53, v53
	v_rcp_f32_e32 v44, v44
	v_rcp_f32_e32 v45, v45
	v_pk_mul_f32 v[34:35], v[38:39], v[34:35]
	v_pk_add_f32 v[52:53], v[52:53], 1.0 op_sel_hi:[1,0]
	v_pk_mul_f32 v[40:41], v[40:41], v[50:51] op_sel_hi:[1,0]
	v_pk_mul_f32 v[42:43], v[42:43], v[44:45]
	v_pk_mul_f32 v[44:45], v[36:37], v[48:49] op_sel_hi:[1,0]
	v_pk_mul_f32 v[36:37], v[38:39], v[48:49] op_sel_hi:[1,0]
	v_exp_f32_e32 v44, v44
	v_exp_f32_e32 v45, v45
	v_exp_f32_e32 v36, v36
	v_exp_f32_e32 v37, v37
	v_rcp_f32_e32 v52, v52
	v_pk_add_f32 v[44:45], v[44:45], 1.0 op_sel_hi:[1,0]
	v_rcp_f32_e32 v53, v53
	v_pk_add_f32 v[36:37], v[36:37], 1.0 op_sel_hi:[1,0]
	v_rcp_f32_e32 v44, v44
	v_rcp_f32_e32 v45, v45
	v_rcp_f32_e32 v36, v36
	v_rcp_f32_e32 v37, v37
	v_pk_mul_f32 v[32:33], v[32:33], v[50:51] op_sel_hi:[1,0]
	v_pk_mul_f32 v[34:35], v[34:35], v[50:51] op_sel_hi:[1,0]
	v_pk_mul_f32 v[40:41], v[40:41], v[52:53]
	v_pk_mul_f32 v[32:33], v[32:33], v[44:45]
	v_pk_mul_f32 v[34:35], v[34:35], v[36:37]
	v_mov_b32_e32 v36, 0
	v_mov_b32_e32 v37, 0
	v_cvt_pk_fp8_f32 v36, v40, v41
	v_cvt_pk_fp8_f32 v37, v32, v33
	v_add_u32_e32 v32, 0x90, v148
	v_mad_i64_i32 v[32:33], s[14:15], v32, s18, v[112:113]
	v_cvt_pk_fp8_f32 v36, v42, v43 op_sel:[0,0,1]
	v_cvt_pk_fp8_f32 v37, v34, v35 op_sel:[0,0,1]
	v_lshl_add_u64 v[32:33], v[32:33], 0, v[134:135]
	v_pk_mul_f32 v[24:25], v[28:29], v[24:25]
	v_mul_f32_e32 v34, v136, v136
	global_store_dwordx2 v[32:33], v[36:37], off
	v_mul_f32_e32 v32, 0xbfb8aa3b, v136
	v_pk_mul_f32 v[36:37], v[28:29], v[32:33] op_sel_hi:[1,0]
	v_pk_mul_f32 v[28:29], v[30:31], v[32:33] op_sel_hi:[1,0]
	v_pk_mul_f32 v[26:27], v[30:31], v[26:27]
	v_exp_f32_e32 v28, v28
	v_exp_f32_e32 v29, v29
	v_pk_mul_f32 v[26:27], v[26:27], v[34:35] op_sel_hi:[1,0]
	v_pk_mul_f32 v[16:17], v[20:21], v[16:17]
	v_exp_f32_e32 v36, v36
	v_pk_add_f32 v[28:29], v[28:29], 1.0 op_sel_hi:[1,0]
	v_exp_f32_e32 v37, v37
	v_rcp_f32_e32 v28, v28
	v_rcp_f32_e32 v29, v29
	v_pk_mul_f32 v[18:19], v[22:23], v[18:19]
	v_pk_add_f32 v[36:37], v[36:37], 1.0 op_sel_hi:[1,0]
	v_pk_mul_f32 v[24:25], v[24:25], v[34:35] op_sel_hi:[1,0]
	v_pk_mul_f32 v[26:27], v[26:27], v[28:29]
	v_pk_mul_f32 v[28:29], v[20:21], v[32:33] op_sel_hi:[1,0]
	v_pk_mul_f32 v[20:21], v[22:23], v[32:33] op_sel_hi:[1,0]
	v_exp_f32_e32 v28, v28
	v_exp_f32_e32 v29, v29
	v_exp_f32_e32 v20, v20
	v_exp_f32_e32 v21, v21
	v_rcp_f32_e32 v36, v36
	v_pk_add_f32 v[28:29], v[28:29], 1.0 op_sel_hi:[1,0]
	v_rcp_f32_e32 v37, v37
	v_pk_add_f32 v[20:21], v[20:21], 1.0 op_sel_hi:[1,0]
	v_rcp_f32_e32 v28, v28
	v_rcp_f32_e32 v29, v29
	v_rcp_f32_e32 v20, v20
	v_rcp_f32_e32 v21, v21
	v_pk_mul_f32 v[16:17], v[16:17], v[34:35] op_sel_hi:[1,0]
	v_pk_mul_f32 v[18:19], v[18:19], v[34:35] op_sel_hi:[1,0]
	v_pk_mul_f32 v[24:25], v[24:25], v[36:37]
	v_pk_mul_f32 v[16:17], v[16:17], v[28:29]
	v_pk_mul_f32 v[18:19], v[18:19], v[20:21]
	v_mov_b32_e32 v20, 0
	v_mov_b32_e32 v21, 0
	v_cvt_pk_fp8_f32 v20, v24, v25
	v_cvt_pk_fp8_f32 v21, v16, v17
	v_add_u32_e32 v16, 0xa0, v148
	v_mad_i64_i32 v[16:17], s[14:15], v16, s18, v[112:113]
	v_cvt_pk_fp8_f32 v20, v26, v27 op_sel:[0,0,1]
	v_cvt_pk_fp8_f32 v21, v18, v19 op_sel:[0,0,1]
	v_lshl_add_u64 v[16:17], v[16:17], 0, v[134:135]
	v_pk_mul_f32 v[8:9], v[12:13], v[8:9]
	v_mul_f32_e32 v18, v137, v137
	global_store_dwordx2 v[16:17], v[20:21], off
	v_mul_f32_e32 v16, 0xbfb8aa3b, v137
	v_pk_mul_f32 v[20:21], v[12:13], v[16:17] op_sel_hi:[1,0]
	v_pk_mul_f32 v[12:13], v[14:15], v[16:17] op_sel_hi:[1,0]
	v_pk_mul_f32 v[10:11], v[14:15], v[10:11]
	v_exp_f32_e32 v12, v12
	v_exp_f32_e32 v13, v13
	v_pk_mul_f32 v[10:11], v[10:11], v[18:19] op_sel_hi:[1,0]
	v_pk_mul_f32 v[0:1], v[4:5], v[0:1]
	v_exp_f32_e32 v20, v20
	v_pk_add_f32 v[12:13], v[12:13], 1.0 op_sel_hi:[1,0]
	v_exp_f32_e32 v21, v21
	v_rcp_f32_e32 v12, v12
	v_rcp_f32_e32 v13, v13
	v_pk_mul_f32 v[2:3], v[6:7], v[2:3]
	v_pk_add_f32 v[20:21], v[20:21], 1.0 op_sel_hi:[1,0]
	v_pk_mul_f32 v[8:9], v[8:9], v[18:19] op_sel_hi:[1,0]
	v_pk_mul_f32 v[10:11], v[10:11], v[12:13]
	v_pk_mul_f32 v[12:13], v[4:5], v[16:17] op_sel_hi:[1,0]
	v_pk_mul_f32 v[4:5], v[6:7], v[16:17] op_sel_hi:[1,0]
	v_exp_f32_e32 v12, v12
	v_exp_f32_e32 v13, v13
	v_exp_f32_e32 v4, v4
	v_exp_f32_e32 v5, v5
	v_rcp_f32_e32 v20, v20
	v_pk_add_f32 v[12:13], v[12:13], 1.0 op_sel_hi:[1,0]
	v_rcp_f32_e32 v21, v21
	v_pk_add_f32 v[4:5], v[4:5], 1.0 op_sel_hi:[1,0]
	v_rcp_f32_e32 v12, v12
	v_rcp_f32_e32 v13, v13
	v_rcp_f32_e32 v4, v4
	v_rcp_f32_e32 v5, v5
	v_pk_mul_f32 v[0:1], v[0:1], v[18:19] op_sel_hi:[1,0]
	v_pk_mul_f32 v[2:3], v[2:3], v[18:19] op_sel_hi:[1,0]
	v_pk_mul_f32 v[8:9], v[8:9], v[20:21]
	v_pk_mul_f32 v[0:1], v[0:1], v[12:13]
	v_pk_mul_f32 v[2:3], v[2:3], v[4:5]
	v_mov_b32_e32 v4, 0
	v_mov_b32_e32 v5, 0
	v_cvt_pk_fp8_f32 v4, v8, v9
	v_cvt_pk_fp8_f32 v5, v0, v1
	v_add_u32_e32 v0, 0xb0, v148
	v_mad_i64_i32 v[0:1], s[14:15], v0, s18, v[112:113]
	v_cvt_pk_fp8_f32 v4, v10, v11 op_sel:[0,0,1]
	v_cvt_pk_fp8_f32 v5, v2, v3 op_sel:[0,0,1]
	v_lshl_add_u64 v[0:1], v[0:1], 0, v[134:135]
	s_mov_b64 s[14:15], -1
	s_andn2_b64 vcc, exec, s[38:39]
	global_store_dwordx2 v[0:1], v[4:5], off
	s_cbranch_vccnz .LBB0_477
	s_lshl_b32 s14, s40, 8
	s_ashr_i32 s15, s14, 31
	v_lshl_add_u64 v[0:1], s[14:15], 2, v[132:133]
	global_load_dword v134, v[0:1], off
	s_andn2_b64 vcc, exec, s[8:9]
	s_cbranch_vccnz .LBB0_476
	s_barrier
	s_branch .LBB0_476

.LBB0_508:
	s_or_b64 exec, exec, s[14:15]
	s_waitcnt lgkmcnt(0)
	s_barrier
	ds_read2_b32 v[12:13], v174 offset1:16
	ds_read2_b32 v[8:9], v174 offset0:32 offset1:48
	ds_read2_b32 v[6:7], v174 offset0:128 offset1:144
	ds_read2_b32 v[2:3], v174 offset0:160 offset1:176
	v_pk_mul_f32 v[18:19], v[156:157], v[152:153]
	s_waitcnt lgkmcnt(0)
	v_mul_f32_e32 v5, 0x3d000000, v12
	v_mul_f32_e32 v4, 0xbfb8aa3b, v5
	v_pk_mul_f32 v[14:15], v[156:157], v[4:5] op_sel_hi:[1,0]
	v_mul_f32_e32 v12, v5, v5
	v_exp_f32_e32 v14, v14
	v_exp_f32_e32 v15, v15
	v_pk_mul_f32 v[18:19], v[18:19], v[12:13] op_sel_hi:[1,0]
	v_pk_mul_f32 v[16:17], v[158:159], v[154:155]
	v_pk_mul_f32 v[20:21], v[150:151], v[146:147]
	v_pk_add_f32 v[14:15], v[14:15], 1.0 op_sel_hi:[1,0]
	v_pk_mul_f32 v[16:17], v[16:17], v[12:13] op_sel_hi:[1,0]
	v_rcp_f32_e32 v14, v14
	v_rcp_f32_e32 v15, v15
	v_pk_mul_f32 v[20:21], v[20:21], v[12:13] op_sel_hi:[1,0]
	v_pk_mul_f32 v[22:23], v[148:149], v[144:145]
	v_mul_f32_e32 v11, 0x3d000000, v13
	v_pk_mul_f32 v[14:15], v[18:19], v[14:15]
	v_pk_mul_f32 v[18:19], v[158:159], v[4:5] op_sel_hi:[1,0]
	v_pk_mul_f32 v[22:23], v[22:23], v[12:13] op_sel_hi:[1,0]
	v_exp_f32_e32 v18, v18
	v_exp_f32_e32 v19, v19
	v_mul_f32_e32 v12, 0xbfb8aa3b, v11
	v_lshl_add_u32 v10, s30, 8, v171
	v_lshl_or_b32 v0, s29, 7, v175
	v_pk_add_f32 v[18:19], v[18:19], 1.0 op_sel_hi:[1,0]
	v_ashrrev_i32_e32 v1, 31, v0
	v_rcp_f32_e32 v18, v18
	v_rcp_f32_e32 v19, v19
	v_pk_mul_f32 v[24:25], v[132:133], v[128:129]
	s_andn2_b64 vcc, exec, s[40:41]
	v_pk_mul_f32 v[16:17], v[16:17], v[18:19]
	v_pk_mul_f32 v[18:19], v[148:149], v[4:5] op_sel_hi:[1,0]
	v_pk_mul_f32 v[4:5], v[150:151], v[4:5] op_sel_hi:[1,0]
	v_exp_f32_e32 v18, v18
	v_exp_f32_e32 v4, v4
	v_exp_f32_e32 v5, v5
	v_exp_f32_e32 v19, v19
	v_pk_add_f32 v[4:5], v[4:5], 1.0 op_sel_hi:[1,0]
	s_nop 0
	v_rcp_f32_e32 v4, v4
	v_rcp_f32_e32 v5, v5
	v_pk_add_f32 v[18:19], v[18:19], 1.0 op_sel_hi:[1,0]
	v_pk_mul_f32 v[4:5], v[20:21], v[4:5]
	v_rcp_f32_e32 v18, v18
	v_rcp_f32_e32 v19, v19
	v_mov_b32_e32 v20, 0
	v_cvt_pk_fp8_f32 v20, v14, v15
	v_mov_b32_e32 v21, 0
	v_pk_mul_f32 v[18:19], v[22:23], v[18:19]
	v_pk_mul_f32 v[22:23], v[134:135], v[130:131]
	v_cvt_pk_fp8_f32 v20, v16, v17 op_sel:[0,0,1]
	v_cvt_pk_fp8_f32 v21, v18, v19
	v_pk_mul_f32 v[16:17], v[140:141], v[12:13] op_sel_hi:[1,0]
	v_pk_mul_f32 v[18:19], v[142:143], v[138:139]
	v_exp_f32_e32 v16, v16
	v_exp_f32_e32 v17, v17
	v_cvt_pk_fp8_f32 v21, v4, v5 op_sel:[0,0,1]
	v_mov_b64_e32 v[4:5], s[72:73]
	v_mad_i64_i32 v[14:15], s[14:15], v10, s18, v[4:5]
	v_pk_add_f32 v[16:17], v[16:17], 1.0 op_sel_hi:[1,0]
	v_lshl_add_u64 v[14:15], v[14:15], 0, v[0:1]
	v_rcp_f32_e32 v16, v16
	v_rcp_f32_e32 v17, v17
	global_store_dwordx2 v[14:15], v[20:21], off
	v_mul_f32_e32 v14, v11, v11
	v_pk_mul_f32 v[20:21], v[140:141], v[136:137]
	v_pk_mul_f32 v[18:19], v[18:19], v[14:15] op_sel_hi:[1,0]
	v_pk_mul_f32 v[20:21], v[20:21], v[14:15] op_sel_hi:[1,0]
	v_pk_mul_f32 v[24:25], v[24:25], v[14:15] op_sel_hi:[1,0]
	v_pk_mul_f32 v[16:17], v[20:21], v[16:17]
	v_pk_mul_f32 v[20:21], v[142:143], v[12:13] op_sel_hi:[1,0]
	v_pk_mul_f32 v[14:15], v[22:23], v[14:15] op_sel_hi:[1,0]
	v_exp_f32_e32 v20, v20
	v_exp_f32_e32 v21, v21
	v_or_b32_e32 v11, 16, v10
	v_pk_mul_f32 v[22:23], v[116:117], v[112:113]
	v_pk_add_f32 v[20:21], v[20:21], 1.0 op_sel_hi:[1,0]
	s_nop 0
	v_rcp_f32_e32 v20, v20
	v_rcp_f32_e32 v21, v21
	s_nop 0
	v_pk_mul_f32 v[18:19], v[18:19], v[20:21]
	v_pk_mul_f32 v[20:21], v[132:133], v[12:13] op_sel_hi:[1,0]
	v_pk_mul_f32 v[12:13], v[134:135], v[12:13] op_sel_hi:[1,0]
	v_exp_f32_e32 v20, v20
	v_exp_f32_e32 v21, v21
	v_exp_f32_e32 v12, v12
	v_exp_f32_e32 v13, v13
	v_pk_add_f32 v[20:21], v[20:21], 1.0 op_sel_hi:[1,0]
	s_nop 0
	v_rcp_f32_e32 v20, v20
	v_pk_add_f32 v[12:13], v[12:13], 1.0 op_sel_hi:[1,0]
	v_rcp_f32_e32 v21, v21
	v_rcp_f32_e32 v12, v12
	v_rcp_f32_e32 v13, v13
	v_pk_mul_f32 v[20:21], v[24:25], v[20:21]
	v_pk_mul_f32 v[12:13], v[14:15], v[12:13]
	v_mov_b32_e32 v14, 0
	v_mov_b32_e32 v15, 0
	v_cvt_pk_fp8_f32 v14, v16, v17
	v_cvt_pk_fp8_f32 v15, v20, v21
	v_pk_mul_f32 v[16:17], v[126:127], v[122:123]
	v_pk_mul_f32 v[20:21], v[118:119], v[114:115]
	v_cvt_pk_fp8_f32 v14, v18, v19 op_sel:[0,0,1]
	v_cvt_pk_fp8_f32 v15, v12, v13 op_sel:[0,0,1]
	v_mad_i64_i32 v[12:13], s[14:15], v11, s18, v[4:5]
	v_mul_f32_e32 v11, 0x3d000000, v8
	v_lshl_add_u64 v[12:13], v[12:13], 0, v[0:1]
	v_mul_f32_e32 v8, 0xbfb8aa3b, v11
	global_store_dwordx2 v[12:13], v[14:15], off
	v_pk_mul_f32 v[14:15], v[124:125], v[8:9] op_sel_hi:[1,0]
	v_mul_f32_e32 v12, v11, v11
	v_exp_f32_e32 v14, v14
	v_exp_f32_e32 v15, v15
	v_pk_mul_f32 v[18:19], v[124:125], v[120:121]
	v_pk_mul_f32 v[16:17], v[16:17], v[12:13] op_sel_hi:[1,0]
	v_pk_mul_f32 v[18:19], v[18:19], v[12:13] op_sel_hi:[1,0]
	v_pk_add_f32 v[14:15], v[14:15], 1.0 op_sel_hi:[1,0]
	v_pk_mul_f32 v[22:23], v[22:23], v[12:13] op_sel_hi:[1,0]
	v_rcp_f32_e32 v14, v14
	v_rcp_f32_e32 v15, v15
	v_pk_mul_f32 v[12:13], v[20:21], v[12:13] op_sel_hi:[1,0]
	v_mov_b32_e32 v21, 0
	v_mov_b32_e32 v20, 0
	v_pk_mul_f32 v[14:15], v[18:19], v[14:15]
	v_pk_mul_f32 v[18:19], v[126:127], v[8:9] op_sel_hi:[1,0]
	v_cvt_pk_fp8_f32 v20, v14, v15
	v_exp_f32_e32 v18, v18
	v_exp_f32_e32 v19, v19
	v_add_u32_e32 v11, 0x80, v10
	v_pk_add_f32 v[18:19], v[18:19], 1.0 op_sel_hi:[1,0]
	s_nop 0
	v_rcp_f32_e32 v18, v18
	v_rcp_f32_e32 v19, v19
	s_nop 0
	v_pk_mul_f32 v[16:17], v[16:17], v[18:19]
	v_pk_mul_f32 v[18:19], v[116:117], v[8:9] op_sel_hi:[1,0]
	v_cvt_pk_fp8_f32 v20, v16, v17 op_sel:[0,0,1]
	v_exp_f32_e32 v18, v18
	v_exp_f32_e32 v19, v19
	v_pk_mul_f32 v[16:17], v[110:111], v[106:107]
	v_pk_add_f32 v[18:19], v[18:19], 1.0 op_sel_hi:[1,0]
	s_nop 0
	v_rcp_f32_e32 v18, v18
	v_rcp_f32_e32 v19, v19
	s_nop 0
	v_pk_mul_f32 v[18:19], v[22:23], v[18:19]
	v_pk_mul_f32 v[22:23], v[118:119], v[8:9] op_sel_hi:[1,0]
	v_cvt_pk_fp8_f32 v21, v18, v19
	v_exp_f32_e32 v22, v22
	v_exp_f32_e32 v23, v23
	v_or_b32_e32 v8, 32, v10
	v_mul_f32_e32 v9, 0x3d000000, v9
	v_pk_mul_f32 v[18:19], v[108:109], v[104:105]
	v_pk_add_f32 v[22:23], v[22:23], 1.0 op_sel_hi:[1,0]
	s_nop 0
	v_rcp_f32_e32 v22, v22
	v_rcp_f32_e32 v23, v23
	s_nop 0
	v_pk_mul_f32 v[12:13], v[12:13], v[22:23]
	s_nop 0
	v_cvt_pk_fp8_f32 v21, v12, v13 op_sel:[0,0,1]
	v_mad_i64_i32 v[12:13], s[14:15], v8, s18, v[4:5]
	v_mul_f32_e32 v8, 0xbfb8aa3b, v9
	v_pk_mul_f32 v[14:15], v[108:109], v[8:9] op_sel_hi:[1,0]
	v_lshl_add_u64 v[12:13], v[12:13], 0, v[0:1]
	v_exp_f32_e32 v14, v14
	v_exp_f32_e32 v15, v15
	global_store_dwordx2 v[12:13], v[20:21], off
	v_mul_f32_e32 v12, v9, v9
	v_pk_mul_f32 v[18:19], v[18:19], v[12:13] op_sel_hi:[1,0]
	v_pk_add_f32 v[14:15], v[14:15], 1.0 op_sel_hi:[1,0]
	v_pk_mul_f32 v[16:17], v[16:17], v[12:13] op_sel_hi:[1,0]
	v_rcp_f32_e32 v14, v14
	v_rcp_f32_e32 v15, v15
	v_pk_mul_f32 v[20:21], v[102:103], v[98:99]
	v_pk_mul_f32 v[22:23], v[100:101], v[96:97]
	v_pk_mul_f32 v[14:15], v[18:19], v[14:15]
	v_pk_mul_f32 v[18:19], v[110:111], v[8:9] op_sel_hi:[1,0]
	v_pk_mul_f32 v[22:23], v[22:23], v[12:13] op_sel_hi:[1,0]
	v_exp_f32_e32 v18, v18
	v_exp_f32_e32 v19, v19
	v_pk_mul_f32 v[12:13], v[20:21], v[12:13] op_sel_hi:[1,0]
	v_pk_mul_f32 v[20:21], v[84:85], v[80:81]
	v_pk_add_f32 v[18:19], v[18:19], 1.0 op_sel_hi:[1,0]
	s_nop 0
	v_rcp_f32_e32 v18, v18
	v_rcp_f32_e32 v19, v19
	s_nop 0
	v_pk_mul_f32 v[16:17], v[16:17], v[18:19]
	v_pk_mul_f32 v[18:19], v[100:101], v[8:9] op_sel_hi:[1,0]
	v_pk_mul_f32 v[8:9], v[102:103], v[8:9] op_sel_hi:[1,0]
	v_exp_f32_e32 v18, v18
	v_exp_f32_e32 v19, v19
	v_exp_f32_e32 v8, v8
	v_exp_f32_e32 v9, v9
	v_pk_add_f32 v[18:19], v[18:19], 1.0 op_sel_hi:[1,0]
	s_nop 0
	v_rcp_f32_e32 v18, v18
	v_pk_add_f32 v[8:9], v[8:9], 1.0 op_sel_hi:[1,0]
	v_rcp_f32_e32 v19, v19
	v_rcp_f32_e32 v8, v8
	v_rcp_f32_e32 v9, v9
	v_pk_mul_f32 v[18:19], v[22:23], v[18:19]
	v_pk_mul_f32 v[8:9], v[12:13], v[8:9]
	v_mov_b32_e32 v12, 0
	v_mov_b32_e32 v13, 0
	v_cvt_pk_fp8_f32 v12, v14, v15
	v_cvt_pk_fp8_f32 v13, v18, v19
	v_pk_mul_f32 v[14:15], v[94:95], v[90:91]
	v_pk_mul_f32 v[18:19], v[86:87], v[82:83]
	v_cvt_pk_fp8_f32 v12, v16, v17 op_sel:[0,0,1]
	v_cvt_pk_fp8_f32 v13, v8, v9 op_sel:[0,0,1]
	v_or_b32_e32 v8, 48, v10
	v_mad_i64_i32 v[8:9], s[14:15], v8, s18, v[4:5]
	v_lshl_add_u64 v[8:9], v[8:9], 0, v[0:1]
	global_store_dwordx2 v[8:9], v[12:13], off
	v_mul_f32_e32 v8, 0x3d000000, v6
	v_mul_f32_e32 v6, 0xbfb8aa3b, v8
	v_pk_mul_f32 v[12:13], v[92:93], v[6:7] op_sel_hi:[1,0]
	v_mul_f32_e32 v8, v8, v8
	v_exp_f32_e32 v12, v12
	v_exp_f32_e32 v13, v13
	v_pk_mul_f32 v[16:17], v[92:93], v[88:89]
	v_pk_mul_f32 v[14:15], v[14:15], v[8:9] op_sel_hi:[1,0]
	v_pk_mul_f32 v[16:17], v[16:17], v[8:9] op_sel_hi:[1,0]
	v_pk_add_f32 v[12:13], v[12:13], 1.0 op_sel_hi:[1,0]
	v_pk_mul_f32 v[20:21], v[20:21], v[8:9] op_sel_hi:[1,0]
	v_rcp_f32_e32 v12, v12
	v_rcp_f32_e32 v13, v13
	v_pk_mul_f32 v[8:9], v[18:19], v[8:9] op_sel_hi:[1,0]
	v_mov_b32_e32 v18, 0
	v_mov_b32_e32 v19, 0
	v_pk_mul_f32 v[12:13], v[16:17], v[12:13]
	v_pk_mul_f32 v[16:17], v[94:95], v[6:7] op_sel_hi:[1,0]
	v_cvt_pk_fp8_f32 v18, v12, v13
	v_exp_f32_e32 v16, v16
	v_exp_f32_e32 v17, v17
	s_nop 0
	v_pk_add_f32 v[16:17], v[16:17], 1.0 op_sel_hi:[1,0]
	s_nop 0
	v_rcp_f32_e32 v16, v16
	v_rcp_f32_e32 v17, v17
	s_nop 0
	v_pk_mul_f32 v[14:15], v[14:15], v[16:17]
	v_pk_mul_f32 v[16:17], v[84:85], v[6:7] op_sel_hi:[1,0]
	v_cvt_pk_fp8_f32 v18, v14, v15 op_sel:[0,0,1]
	v_exp_f32_e32 v16, v16
	v_exp_f32_e32 v17, v17
	v_pk_mul_f32 v[14:15], v[78:79], v[74:75]
	v_pk_add_f32 v[16:17], v[16:17], 1.0 op_sel_hi:[1,0]
	s_nop 0
	v_rcp_f32_e32 v16, v16
	v_rcp_f32_e32 v17, v17
	s_nop 0
	v_pk_mul_f32 v[16:17], v[20:21], v[16:17]
	v_pk_mul_f32 v[20:21], v[86:87], v[6:7] op_sel_hi:[1,0]
	v_mul_f32_e32 v7, 0x3d000000, v7
	v_exp_f32_e32 v20, v20
	v_exp_f32_e32 v21, v21
	v_mul_f32_e32 v6, 0xbfb8aa3b, v7
	v_cvt_pk_fp8_f32 v19, v16, v17
	v_pk_mul_f32 v[12:13], v[76:77], v[6:7] op_sel_hi:[1,0]
	v_pk_add_f32 v[20:21], v[20:21], 1.0 op_sel_hi:[1,0]
	v_exp_f32_e32 v12, v12
	v_rcp_f32_e32 v20, v20
	v_rcp_f32_e32 v21, v21
	v_exp_f32_e32 v13, v13
	v_pk_mul_f32 v[16:17], v[76:77], v[72:73]
	v_pk_mul_f32 v[8:9], v[8:9], v[20:21]
	s_nop 0
	v_cvt_pk_fp8_f32 v19, v8, v9 op_sel:[0,0,1]
	v_pk_add_f32 v[12:13], v[12:13], 1.0 op_sel_hi:[1,0]
	v_mad_i64_i32 v[8:9], s[14:15], v11, s18, v[4:5]
	v_rcp_f32_e32 v12, v12
	v_rcp_f32_e32 v13, v13
	v_lshl_add_u64 v[8:9], v[8:9], 0, v[0:1]
	global_store_dwordx2 v[8:9], v[18:19], off
	v_mul_f32_e32 v8, v7, v7
	v_pk_mul_f32 v[16:17], v[16:17], v[8:9] op_sel_hi:[1,0]
	v_pk_mul_f32 v[14:15], v[14:15], v[8:9] op_sel_hi:[1,0]
	v_pk_mul_f32 v[12:13], v[16:17], v[12:13]
	v_pk_mul_f32 v[16:17], v[78:79], v[6:7] op_sel_hi:[1,0]
	v_pk_mul_f32 v[18:19], v[70:71], v[66:67]
	v_exp_f32_e32 v16, v16
	v_exp_f32_e32 v17, v17
	v_pk_mul_f32 v[20:21], v[68:69], v[64:65]
	v_pk_add_f32 v[16:17], v[16:17], 1.0 op_sel_hi:[1,0]
	s_nop 0
	v_rcp_f32_e32 v16, v16
	v_rcp_f32_e32 v17, v17
	v_pk_mul_f32 v[20:21], v[20:21], v[8:9] op_sel_hi:[1,0]
	v_pk_mul_f32 v[8:9], v[18:19], v[8:9] op_sel_hi:[1,0]
	v_pk_mul_f32 v[18:19], v[52:53], v[48:49]
	v_pk_mul_f32 v[14:15], v[14:15], v[16:17]
	v_pk_mul_f32 v[16:17], v[68:69], v[6:7] op_sel_hi:[1,0]
	v_pk_mul_f32 v[6:7], v[70:71], v[6:7] op_sel_hi:[1,0]
	v_exp_f32_e32 v16, v16
	v_exp_f32_e32 v17, v17
	v_exp_f32_e32 v6, v6
	v_exp_f32_e32 v7, v7
	v_pk_add_f32 v[16:17], v[16:17], 1.0 op_sel_hi:[1,0]
	s_nop 0
	v_rcp_f32_e32 v16, v16
	v_pk_add_f32 v[6:7], v[6:7], 1.0 op_sel_hi:[1,0]
	v_rcp_f32_e32 v17, v17
	v_rcp_f32_e32 v6, v6
	v_rcp_f32_e32 v7, v7
	v_pk_mul_f32 v[16:17], v[20:21], v[16:17]
	v_pk_mul_f32 v[6:7], v[8:9], v[6:7]
	v_mov_b32_e32 v8, 0
	v_mov_b32_e32 v9, 0
	v_cvt_pk_fp8_f32 v8, v12, v13
	v_cvt_pk_fp8_f32 v9, v16, v17
	v_pk_mul_f32 v[12:13], v[62:63], v[58:59]
	v_pk_mul_f32 v[16:17], v[54:55], v[50:51]
	v_cvt_pk_fp8_f32 v8, v14, v15 op_sel:[0,0,1]
	v_cvt_pk_fp8_f32 v9, v6, v7 op_sel:[0,0,1]
	v_add_u32_e32 v6, 0x90, v10
	v_mad_i64_i32 v[6:7], s[14:15], v6, s18, v[4:5]
	v_lshl_add_u64 v[6:7], v[6:7], 0, v[0:1]
	global_store_dwordx2 v[6:7], v[8:9], off
	v_mul_f32_e32 v6, 0x3d000000, v2
	v_mul_f32_e32 v2, 0xbfb8aa3b, v6
	v_pk_mul_f32 v[8:9], v[60:61], v[2:3] op_sel_hi:[1,0]
	v_mul_f32_e32 v6, v6, v6
	v_exp_f32_e32 v8, v8
	v_exp_f32_e32 v9, v9
	v_pk_mul_f32 v[14:15], v[60:61], v[56:57]
	v_pk_mul_f32 v[12:13], v[12:13], v[6:7] op_sel_hi:[1,0]
	v_pk_mul_f32 v[14:15], v[14:15], v[6:7] op_sel_hi:[1,0]
	v_pk_add_f32 v[8:9], v[8:9], 1.0 op_sel_hi:[1,0]
	v_pk_mul_f32 v[18:19], v[18:19], v[6:7] op_sel_hi:[1,0]
	v_rcp_f32_e32 v8, v8
	v_rcp_f32_e32 v9, v9
	v_pk_mul_f32 v[6:7], v[16:17], v[6:7] op_sel_hi:[1,0]
	v_mov_b32_e32 v17, 0
	v_mov_b32_e32 v16, 0
	v_pk_mul_f32 v[8:9], v[14:15], v[8:9]
	v_pk_mul_f32 v[14:15], v[62:63], v[2:3] op_sel_hi:[1,0]
	v_cvt_pk_fp8_f32 v16, v8, v9
	v_exp_f32_e32 v14, v14
	v_exp_f32_e32 v15, v15
	s_nop 0
	v_pk_add_f32 v[14:15], v[14:15], 1.0 op_sel_hi:[1,0]
	s_nop 0
	v_rcp_f32_e32 v14, v14
	v_rcp_f32_e32 v15, v15
	s_nop 0
	v_pk_mul_f32 v[12:13], v[12:13], v[14:15]
	v_pk_mul_f32 v[14:15], v[52:53], v[2:3] op_sel_hi:[1,0]
	v_cvt_pk_fp8_f32 v16, v12, v13 op_sel:[0,0,1]
	v_exp_f32_e32 v14, v14
	v_exp_f32_e32 v15, v15
	v_pk_mul_f32 v[12:13], v[46:47], v[42:43]
	v_pk_add_f32 v[14:15], v[14:15], 1.0 op_sel_hi:[1,0]
	s_nop 0
	v_rcp_f32_e32 v14, v14
	v_rcp_f32_e32 v15, v15
	s_nop 0
	v_pk_mul_f32 v[14:15], v[18:19], v[14:15]
	v_pk_mul_f32 v[18:19], v[54:55], v[2:3] op_sel_hi:[1,0]
	v_cvt_pk_fp8_f32 v17, v14, v15
	v_exp_f32_e32 v18, v18
	v_exp_f32_e32 v19, v19
	v_add_u32_e32 v2, 0xa0, v10
	v_mul_f32_e32 v3, 0x3d000000, v3
	v_pk_mul_f32 v[14:15], v[44:45], v[40:41]
	v_pk_add_f32 v[18:19], v[18:19], 1.0 op_sel_hi:[1,0]
	s_nop 0
	v_rcp_f32_e32 v18, v18
	v_rcp_f32_e32 v19, v19
	s_nop 0
	v_pk_mul_f32 v[6:7], v[6:7], v[18:19]
	s_nop 0
	v_cvt_pk_fp8_f32 v17, v6, v7 op_sel:[0,0,1]
	v_mad_i64_i32 v[6:7], s[14:15], v2, s18, v[4:5]
	v_mul_f32_e32 v2, 0xbfb8aa3b, v3
	v_pk_mul_f32 v[8:9], v[44:45], v[2:3] op_sel_hi:[1,0]
	v_lshl_add_u64 v[6:7], v[6:7], 0, v[0:1]
	v_exp_f32_e32 v8, v8
	v_exp_f32_e32 v9, v9
	global_store_dwordx2 v[6:7], v[16:17], off
	v_mul_f32_e32 v6, v3, v3
	v_pk_mul_f32 v[14:15], v[14:15], v[6:7] op_sel_hi:[1,0]
	v_pk_add_f32 v[8:9], v[8:9], 1.0 op_sel_hi:[1,0]
	v_pk_mul_f32 v[12:13], v[12:13], v[6:7] op_sel_hi:[1,0]
	v_rcp_f32_e32 v8, v8
	v_rcp_f32_e32 v9, v9
	v_pk_mul_f32 v[16:17], v[38:39], v[34:35]
	v_pk_mul_f32 v[18:19], v[36:37], v[32:33]
	v_pk_mul_f32 v[8:9], v[14:15], v[8:9]
	v_pk_mul_f32 v[14:15], v[46:47], v[2:3] op_sel_hi:[1,0]
	v_pk_mul_f32 v[18:19], v[18:19], v[6:7] op_sel_hi:[1,0]
	v_exp_f32_e32 v14, v14
	v_exp_f32_e32 v15, v15
	v_pk_mul_f32 v[6:7], v[16:17], v[6:7] op_sel_hi:[1,0]
	v_pk_add_f32 v[14:15], v[14:15], 1.0 op_sel_hi:[1,0]
	s_nop 0
	v_rcp_f32_e32 v14, v14
	v_rcp_f32_e32 v15, v15
	s_nop 0
	v_pk_mul_f32 v[12:13], v[12:13], v[14:15]
	v_pk_mul_f32 v[14:15], v[36:37], v[2:3] op_sel_hi:[1,0]
	v_pk_mul_f32 v[2:3], v[38:39], v[2:3] op_sel_hi:[1,0]
	v_exp_f32_e32 v14, v14
	v_exp_f32_e32 v15, v15
	v_exp_f32_e32 v2, v2
	v_exp_f32_e32 v3, v3
	v_pk_add_f32 v[14:15], v[14:15], 1.0 op_sel_hi:[1,0]
	s_nop 0
	v_rcp_f32_e32 v14, v14
	v_pk_add_f32 v[2:3], v[2:3], 1.0 op_sel_hi:[1,0]
	v_rcp_f32_e32 v15, v15
	v_rcp_f32_e32 v2, v2
	v_rcp_f32_e32 v3, v3
	v_pk_mul_f32 v[14:15], v[18:19], v[14:15]
	v_pk_mul_f32 v[2:3], v[6:7], v[2:3]
	v_mov_b32_e32 v6, 0
	v_mov_b32_e32 v7, 0
	v_cvt_pk_fp8_f32 v6, v8, v9
	v_cvt_pk_fp8_f32 v7, v14, v15
	v_cvt_pk_fp8_f32 v6, v12, v13 op_sel:[0,0,1]
	v_cvt_pk_fp8_f32 v7, v2, v3 op_sel:[0,0,1]
	v_add_u32_e32 v2, 0xb0, v10
	v_mad_i64_i32 v[2:3], s[14:15], v2, s18, v[4:5]
	v_lshl_add_u64 v[0:1], v[2:3], 0, v[0:1]
	s_mov_b64 s[14:15], -1
	global_store_dwordx2 v[0:1], v[6:7], off
	s_cbranch_vccnz .LBB0_499
	s_and_b64 vcc, exec, s[36:37]
	s_cbranch_vccnz .LBB0_511
	s_lshl_b32 s14, s12, 8
	s_ashr_i32 s15, s14, 31
	v_lshl_add_u64 v[0:1], s[14:15], 2, v[162:163]
	global_load_dword v170, v[0:1], off
